# v1 + EpiGate epilogue: P/M rows prefetched 5 steps ahead, counted vmcnt, branch-free masked M, batched sigmoids
# baseline (speedup 1.0000x reference)
; __device__ __forceinline__ unsigned cvt_pk_bf16(float lo, float hi) { unsigned r; asm volatile("v_cvt_pk_bf16_f32 %0, %1, %2" : "=v"(r) : "v"(lo), "v"(hi)); return r; }
; __device__ __forceinline__ float fsigmoid(float x) { return __builtin_amdgcn_rcpf(1.f + __expf(-x)); }
;     __device__ __forceinline__ void operator()(const f32x4 (&acc)[2][2][4][2], const Unit& u, int wr, int wc, int fr, int fq) const {
;         const int br = u.pn >> 2, row0 = u.pm * BM + wr * 64 + fr, col0 = (u.pn & 3) * BM + wc * 32 + 8 * fq;
; #pragma unroll
;         for (int bj = 0; bj < 2; ++bj) { const f32x4 b0 = *(const f32x4*)(bg + br * 1024 + col0 + bj * HALF), b1 = *(const f32x4*)(bg + br * 1024 + col0 + bj * HALF + 4);
; #pragma unroll
;             for (int ai = 0; ai < 2; ++ai)
; #pragma unroll
;                 for (int m = 0; m < 4; ++m) { bf16_t* pm_ = G + (size_t)(row0 + ai * HALF + m * 16) * 3072 + col0 + bj * HALF;
;                     const u32x4 pv = *(const u32x4*)(pm_ + br * 1024); u32x4 mv = (u32x4){0u, 0u, 0u, 0u}; if (br) mv = *(const u32x4*)pm_;
;                     const f32x4 v0 = acc[ai][bj][m][0] + b0, v1 = acc[ai][bj][m][1] + b1;
;                     u32x4 w;
;                     w.x = cvt_pk_bf16(bf_lo(mv.x) + fsigmoid(v0[0]) * bf_lo(pv.x), bf_hi(mv.x) + fsigmoid(v0[1]) * bf_hi(pv.x));
;                     w.y = cvt_pk_bf16(bf_lo(mv.y) + fsigmoid(v0[2]) * bf_lo(pv.y), bf_hi(mv.y) + fsigmoid(v0[3]) * bf_hi(pv.y));
;                     w.z = cvt_pk_bf16(bf_lo(mv.z) + fsigmoid(v1[0]) * bf_lo(pv.z), bf_hi(mv.z) + fsigmoid(v1[1]) * bf_hi(pv.z));
;                     w.w = cvt_pk_bf16(bf_lo(mv.w) + fsigmoid(v1[2]) * bf_lo(pv.w), bf_hi(mv.w) + fsigmoid(v1[3]) * bf_hi(pv.w));
;                     *(u32x4*)pm_ = w; } }
.LBB0_278:
	s_lshl_b32 s9, s38, 8
	s_and_b32 s48, s9, 0xfffffc00
	s_and_b32 s13, s9, 0x300
	s_cmp_gt_u32 s38, 3
	s_cselect_b32 s50, -1, 0
	v_lshl_add_u32 v246, s46, 8, v1
	s_ashr_i32 s49, s48, 31
	s_lshl_b64 s[46:47], s[48:49], 2
	s_add_u32 s46, s61, s46
	s_addc_u32 s47, s62, s47
	v_or_b32_e32 v247, s13, v165
	v_mul_lo_u32 v248, v246, s96
	v_lshl_add_u32 v248, v247, 1, v248
	s_lshl_b32 s51, s48, 1
	v_add_u32_e32 v249, s51, v248
	v_lshlrev_b32_e32 v247, 2, v247
	global_load_dwordx4 v[90:93], v247, s[46:47]
	global_load_dwordx4 v[94:97], v247, s[46:47] offset:16
	global_load_dwordx4 v[138:141], v247, s[46:47] offset:512
	global_load_dwordx4 v[142:145], v247, s[46:47] offset:528
	global_load_dwordx4 v[182:185], v249, s[90:91]
	global_load_dwordx4 v[214:217], v248, s[90:91]
	v_add_u32_e32 v147, 0x18000, v249
	global_load_dwordx4 v[198:201], v147, s[90:91]
	v_add_u32_e32 v147, 0x18000, v248
	global_load_dwordx4 v[218:221], v147, s[90:91]
	v_add_u32_e32 v147, 0x30000, v249
	global_load_dwordx4 v[202:205], v147, s[90:91]
	v_add_u32_e32 v147, 0x30000, v248
	global_load_dwordx4 v[222:225], v147, s[90:91]
	v_add_u32_e32 v147, 0x48000, v249
	global_load_dwordx4 v[206:209], v147, s[90:91]
	v_add_u32_e32 v147, 0x48000, v248
	global_load_dwordx4 v[226:229], v147, s[90:91]
	v_add_u32_e32 v147, 0xc0000, v249
	global_load_dwordx4 v[210:213], v147, s[90:91]
	v_add_u32_e32 v147, 0xc0000, v248
	global_load_dwordx4 v[236:239], v147, s[90:91]
	s_waitcnt vmcnt(8)
	v_pk_add_f32 v[134:135], v[134:135], v[90:91]
	v_pk_add_f32 v[136:137], v[136:137], v[92:93]
	v_pk_add_f32 v[130:131], v[130:131], v[94:95]
	v_pk_add_f32 v[132:133], v[132:133], v[96:97]
	v_mul_f32_e32 v134, 0xbfb8aa3b, v134
	v_mul_f32_e32 v135, 0xbfb8aa3b, v135
	v_mul_f32_e32 v136, 0xbfb8aa3b, v136
	v_mul_f32_e32 v137, 0xbfb8aa3b, v137
	v_mul_f32_e32 v130, 0xbfb8aa3b, v130
	v_mul_f32_e32 v131, 0xbfb8aa3b, v131
	v_mul_f32_e32 v132, 0xbfb8aa3b, v132
	v_mul_f32_e32 v133, 0xbfb8aa3b, v133
	v_exp_f32_e32 v134, v134
	v_exp_f32_e32 v135, v135
	v_exp_f32_e32 v136, v136
	v_exp_f32_e32 v137, v137
	v_exp_f32_e32 v130, v130
	v_exp_f32_e32 v131, v131
	v_exp_f32_e32 v132, v132
	v_exp_f32_e32 v133, v133
	v_add_f32_e32 v134, 1.0, v134
	v_add_f32_e32 v135, 1.0, v135
	v_add_f32_e32 v136, 1.0, v136
	v_add_f32_e32 v137, 1.0, v137
	v_add_f32_e32 v130, 1.0, v130
	v_add_f32_e32 v131, 1.0, v131
	v_add_f32_e32 v132, 1.0, v132
	v_add_f32_e32 v133, 1.0, v133
	v_rcp_f32_e32 v134, v134
	v_rcp_f32_e32 v135, v135
	v_rcp_f32_e32 v136, v136
	v_rcp_f32_e32 v137, v137
	v_rcp_f32_e32 v130, v130
	v_rcp_f32_e32 v131, v131
	v_rcp_f32_e32 v132, v132
	v_rcp_f32_e32 v133, v133
	v_and_b32_e32 v214, s50, v214
	v_and_b32_e32 v215, s50, v215
	v_and_b32_e32 v216, s50, v216
	v_and_b32_e32 v217, s50, v217
	v_lshlrev_b32_e32 v150, 16, v182
	v_and_b32_e32 v182, 0xffff0000, v182
	v_lshlrev_b32_e32 v151, 16, v214
	v_and_b32_e32 v214, 0xffff0000, v214
	v_lshlrev_b32_e32 v152, 16, v183
	v_and_b32_e32 v183, 0xffff0000, v183
	v_lshlrev_b32_e32 v153, 16, v215
	v_and_b32_e32 v215, 0xffff0000, v215
	v_lshlrev_b32_e32 v178, 16, v184
	v_and_b32_e32 v184, 0xffff0000, v184
	v_lshlrev_b32_e32 v179, 16, v216
	v_and_b32_e32 v216, 0xffff0000, v216
	v_lshlrev_b32_e32 v180, 16, v185
	v_and_b32_e32 v185, 0xffff0000, v185
	v_lshlrev_b32_e32 v181, 16, v217
	v_and_b32_e32 v217, 0xffff0000, v217
	v_fmac_f32_e32 v151, v134, v150
	v_fmac_f32_e32 v214, v135, v182
	v_fmac_f32_e32 v153, v136, v152
	v_fmac_f32_e32 v215, v137, v183
	v_fmac_f32_e32 v179, v130, v178
	v_fmac_f32_e32 v216, v131, v184
	v_fmac_f32_e32 v181, v132, v180
	v_fmac_f32_e32 v217, v133, v185
	v_cvt_pk_bf16_f32 v214, v151, v214
	v_cvt_pk_bf16_f32 v215, v153, v215
	v_cvt_pk_bf16_f32 v216, v179, v216
	v_cvt_pk_bf16_f32 v217, v181, v217
	global_store_dwordx4 v248, v[214:217], s[90:91]
	v_add_u32_e32 v147, 0xd8000, v249
	global_load_dwordx4 v[134:137], v147, s[90:91]
	v_add_u32_e32 v147, 0xd8000, v248
	global_load_dwordx4 v[130:133], v147, s[90:91]
	s_waitcnt vmcnt(9)
	v_pk_add_f32 v[126:127], v[126:127], v[90:91]
	v_pk_add_f32 v[128:129], v[128:129], v[92:93]
	v_pk_add_f32 v[122:123], v[122:123], v[94:95]
	v_pk_add_f32 v[124:125], v[124:125], v[96:97]
	v_mul_f32_e32 v126, 0xbfb8aa3b, v126
	v_mul_f32_e32 v127, 0xbfb8aa3b, v127
	v_mul_f32_e32 v128, 0xbfb8aa3b, v128
	v_mul_f32_e32 v129, 0xbfb8aa3b, v129
	v_mul_f32_e32 v122, 0xbfb8aa3b, v122
	v_mul_f32_e32 v123, 0xbfb8aa3b, v123
	v_mul_f32_e32 v124, 0xbfb8aa3b, v124
	v_mul_f32_e32 v125, 0xbfb8aa3b, v125
	v_exp_f32_e32 v126, v126
	v_exp_f32_e32 v127, v127
	v_exp_f32_e32 v128, v128
	v_exp_f32_e32 v129, v129
	v_exp_f32_e32 v122, v122
	v_exp_f32_e32 v123, v123
	v_exp_f32_e32 v124, v124
	v_exp_f32_e32 v125, v125
	v_add_f32_e32 v126, 1.0, v126
	v_add_f32_e32 v127, 1.0, v127
	v_add_f32_e32 v128, 1.0, v128
	v_add_f32_e32 v129, 1.0, v129
	v_add_f32_e32 v122, 1.0, v122
	v_add_f32_e32 v123, 1.0, v123
	v_add_f32_e32 v124, 1.0, v124
	v_add_f32_e32 v125, 1.0, v125
	v_rcp_f32_e32 v126, v126
	v_rcp_f32_e32 v127, v127
	v_rcp_f32_e32 v128, v128
	v_rcp_f32_e32 v129, v129
	v_rcp_f32_e32 v122, v122
	v_rcp_f32_e32 v123, v123
	v_rcp_f32_e32 v124, v124
	v_rcp_f32_e32 v125, v125
	v_and_b32_e32 v218, s50, v218
	v_and_b32_e32 v219, s50, v219
	v_and_b32_e32 v220, s50, v220
	v_and_b32_e32 v221, s50, v221
	v_lshlrev_b32_e32 v150, 16, v198
	v_and_b32_e32 v198, 0xffff0000, v198
	v_lshlrev_b32_e32 v151, 16, v218
	v_and_b32_e32 v218, 0xffff0000, v218
	v_lshlrev_b32_e32 v152, 16, v199
	v_and_b32_e32 v199, 0xffff0000, v199
	v_lshlrev_b32_e32 v153, 16, v219
	v_and_b32_e32 v219, 0xffff0000, v219
	v_lshlrev_b32_e32 v178, 16, v200
	v_and_b32_e32 v200, 0xffff0000, v200
	v_lshlrev_b32_e32 v179, 16, v220
	v_and_b32_e32 v220, 0xffff0000, v220
	v_lshlrev_b32_e32 v180, 16, v201
	v_and_b32_e32 v201, 0xffff0000, v201
	v_lshlrev_b32_e32 v181, 16, v221
	v_and_b32_e32 v221, 0xffff0000, v221
	v_fmac_f32_e32 v151, v126, v150
	v_fmac_f32_e32 v218, v127, v198
	v_fmac_f32_e32 v153, v128, v152
	v_fmac_f32_e32 v219, v129, v199
	v_fmac_f32_e32 v179, v122, v178
	v_fmac_f32_e32 v220, v123, v200
	v_fmac_f32_e32 v181, v124, v180
	v_fmac_f32_e32 v221, v125, v201
	v_cvt_pk_bf16_f32 v218, v151, v218
	v_cvt_pk_bf16_f32 v219, v153, v219
	v_cvt_pk_bf16_f32 v220, v179, v220
	v_cvt_pk_bf16_f32 v221, v181, v221
	v_add_u32_e32 v146, 0x18000, v248
	global_store_dwordx4 v146, v[218:221], s[90:91]
	v_add_u32_e32 v147, 0xf0000, v249
	global_load_dwordx4 v[126:129], v147, s[90:91]
	v_add_u32_e32 v147, 0xf0000, v248
	global_load_dwordx4 v[122:125], v147, s[90:91]
	s_waitcnt vmcnt(10)
; __device__ __forceinline__ unsigned cvt_pk_bf16(float lo, float hi) { unsigned r; asm volatile("v_cvt_pk_bf16_f32 %0, %1, %2" : "=v"(r) : "v"(lo), "v"(hi)); return r; }
; __device__ __forceinline__ float fsigmoid(float x) { return __builtin_amdgcn_rcpf(1.f + __expf(-x)); }
;     __device__ __forceinline__ void operator()(const f32x4 (&acc)[2][2][4][2], const Unit& u, int wr, int wc, int fr, int fq) const {
;         const int br = u.pn >> 2, row0 = u.pm * BM + wr * 64 + fr, col0 = (u.pn & 3) * BM + wc * 32 + 8 * fq;
; #pragma unroll
;         for (int bj = 0; bj < 2; ++bj) { const f32x4 b0 = *(const f32x4*)(bg + br * 1024 + col0 + bj * HALF), b1 = *(const f32x4*)(bg + br * 1024 + col0 + bj * HALF + 4);
; #pragma unroll
;             for (int ai = 0; ai < 2; ++ai)
; #pragma unroll
;                 for (int m = 0; m < 4; ++m) { bf16_t* pm_ = G + (size_t)(row0 + ai * HALF + m * 16) * 3072 + col0 + bj * HALF;
;                     const u32x4 pv = *(const u32x4*)(pm_ + br * 1024); u32x4 mv = (u32x4){0u, 0u, 0u, 0u}; if (br) mv = *(const u32x4*)pm_;
;                     const f32x4 v0 = acc[ai][bj][m][0] + b0, v1 = acc[ai][bj][m][1] + b1;
;                     u32x4 w;
;                     w.x = cvt_pk_bf16(bf_lo(mv.x) + fsigmoid(v0[0]) * bf_lo(pv.x), bf_hi(mv.x) + fsigmoid(v0[1]) * bf_hi(pv.x));
;                     w.y = cvt_pk_bf16(bf_lo(mv.y) + fsigmoid(v0[2]) * bf_lo(pv.y), bf_hi(mv.y) + fsigmoid(v0[3]) * bf_hi(pv.y));
;                     w.z = cvt_pk_bf16(bf_lo(mv.z) + fsigmoid(v1[0]) * bf_lo(pv.z), bf_hi(mv.z) + fsigmoid(v1[1]) * bf_hi(pv.z));
;                     w.w = cvt_pk_bf16(bf_lo(mv.w) + fsigmoid(v1[2]) * bf_lo(pv.w), bf_hi(mv.w) + fsigmoid(v1[3]) * bf_hi(pv.w));
;                     *(u32x4*)pm_ = w; } }
	v_pk_add_f32 v[118:119], v[118:119], v[90:91]
	v_pk_add_f32 v[120:121], v[120:121], v[92:93]
	v_pk_add_f32 v[114:115], v[114:115], v[94:95]
	v_pk_add_f32 v[116:117], v[116:117], v[96:97]
	v_mul_f32_e32 v118, 0xbfb8aa3b, v118
	v_mul_f32_e32 v119, 0xbfb8aa3b, v119
	v_mul_f32_e32 v120, 0xbfb8aa3b, v120
	v_mul_f32_e32 v121, 0xbfb8aa3b, v121
	v_mul_f32_e32 v114, 0xbfb8aa3b, v114
	v_mul_f32_e32 v115, 0xbfb8aa3b, v115
	v_mul_f32_e32 v116, 0xbfb8aa3b, v116
	v_mul_f32_e32 v117, 0xbfb8aa3b, v117
	v_exp_f32_e32 v118, v118
	v_exp_f32_e32 v119, v119
	v_exp_f32_e32 v120, v120
	v_exp_f32_e32 v121, v121
	v_exp_f32_e32 v114, v114
	v_exp_f32_e32 v115, v115
	v_exp_f32_e32 v116, v116
	v_exp_f32_e32 v117, v117
	v_add_f32_e32 v118, 1.0, v118
	v_add_f32_e32 v119, 1.0, v119
	v_add_f32_e32 v120, 1.0, v120
	v_add_f32_e32 v121, 1.0, v121
	v_add_f32_e32 v114, 1.0, v114
	v_add_f32_e32 v115, 1.0, v115
	v_add_f32_e32 v116, 1.0, v116
	v_add_f32_e32 v117, 1.0, v117
	v_rcp_f32_e32 v118, v118
	v_rcp_f32_e32 v119, v119
	v_rcp_f32_e32 v120, v120
	v_rcp_f32_e32 v121, v121
	v_rcp_f32_e32 v114, v114
	v_rcp_f32_e32 v115, v115
	v_rcp_f32_e32 v116, v116
	v_rcp_f32_e32 v117, v117
	v_and_b32_e32 v222, s50, v222
	v_and_b32_e32 v223, s50, v223
	v_and_b32_e32 v224, s50, v224
	v_and_b32_e32 v225, s50, v225
	v_lshlrev_b32_e32 v150, 16, v202
	v_and_b32_e32 v202, 0xffff0000, v202
	v_lshlrev_b32_e32 v151, 16, v222
	v_and_b32_e32 v222, 0xffff0000, v222
	v_lshlrev_b32_e32 v152, 16, v203
	v_and_b32_e32 v203, 0xffff0000, v203
	v_lshlrev_b32_e32 v153, 16, v223
	v_and_b32_e32 v223, 0xffff0000, v223
	v_lshlrev_b32_e32 v178, 16, v204
	v_and_b32_e32 v204, 0xffff0000, v204
	v_lshlrev_b32_e32 v179, 16, v224
	v_and_b32_e32 v224, 0xffff0000, v224
	v_lshlrev_b32_e32 v180, 16, v205
	v_and_b32_e32 v205, 0xffff0000, v205
	v_lshlrev_b32_e32 v181, 16, v225
	v_and_b32_e32 v225, 0xffff0000, v225
	v_fmac_f32_e32 v151, v118, v150
	v_fmac_f32_e32 v222, v119, v202
	v_fmac_f32_e32 v153, v120, v152
	v_fmac_f32_e32 v223, v121, v203
	v_fmac_f32_e32 v179, v114, v178
	v_fmac_f32_e32 v224, v115, v204
	v_fmac_f32_e32 v181, v116, v180
	v_fmac_f32_e32 v225, v117, v205
	v_cvt_pk_bf16_f32 v222, v151, v222
	v_cvt_pk_bf16_f32 v223, v153, v223
	v_cvt_pk_bf16_f32 v224, v179, v224
	v_cvt_pk_bf16_f32 v225, v181, v225
	v_add_u32_e32 v146, 0x30000, v248
	global_store_dwordx4 v146, v[222:225], s[90:91]
	v_add_u32_e32 v147, 0x108000, v249
	global_load_dwordx4 v[118:121], v147, s[90:91]
	v_add_u32_e32 v147, 0x108000, v248
	global_load_dwordx4 v[114:117], v147, s[90:91]
	s_waitcnt vmcnt(11)
	v_pk_add_f32 v[110:111], v[110:111], v[90:91]
	v_pk_add_f32 v[112:113], v[112:113], v[92:93]
	v_pk_add_f32 v[106:107], v[106:107], v[94:95]
	v_pk_add_f32 v[108:109], v[108:109], v[96:97]
	v_mul_f32_e32 v110, 0xbfb8aa3b, v110
	v_mul_f32_e32 v111, 0xbfb8aa3b, v111
	v_mul_f32_e32 v112, 0xbfb8aa3b, v112
	v_mul_f32_e32 v113, 0xbfb8aa3b, v113
	v_mul_f32_e32 v106, 0xbfb8aa3b, v106
	v_mul_f32_e32 v107, 0xbfb8aa3b, v107
	v_mul_f32_e32 v108, 0xbfb8aa3b, v108
	v_mul_f32_e32 v109, 0xbfb8aa3b, v109
	v_exp_f32_e32 v110, v110
	v_exp_f32_e32 v111, v111
	v_exp_f32_e32 v112, v112
	v_exp_f32_e32 v113, v113
	v_exp_f32_e32 v106, v106
	v_exp_f32_e32 v107, v107
	v_exp_f32_e32 v108, v108
	v_exp_f32_e32 v109, v109
	v_add_f32_e32 v110, 1.0, v110
	v_add_f32_e32 v111, 1.0, v111
	v_add_f32_e32 v112, 1.0, v112
	v_add_f32_e32 v113, 1.0, v113
	v_add_f32_e32 v106, 1.0, v106
	v_add_f32_e32 v107, 1.0, v107
	v_add_f32_e32 v108, 1.0, v108
	v_add_f32_e32 v109, 1.0, v109
	v_rcp_f32_e32 v110, v110
	v_rcp_f32_e32 v111, v111
	v_rcp_f32_e32 v112, v112
	v_rcp_f32_e32 v113, v113
	v_rcp_f32_e32 v106, v106
	v_rcp_f32_e32 v107, v107
	v_rcp_f32_e32 v108, v108
	v_rcp_f32_e32 v109, v109
	v_and_b32_e32 v226, s50, v226
	v_and_b32_e32 v227, s50, v227
	v_and_b32_e32 v228, s50, v228
	v_and_b32_e32 v229, s50, v229
	v_lshlrev_b32_e32 v150, 16, v206
	v_and_b32_e32 v206, 0xffff0000, v206
	v_lshlrev_b32_e32 v151, 16, v226
	v_and_b32_e32 v226, 0xffff0000, v226
	v_lshlrev_b32_e32 v152, 16, v207
	v_and_b32_e32 v207, 0xffff0000, v207
	v_lshlrev_b32_e32 v153, 16, v227
	v_and_b32_e32 v227, 0xffff0000, v227
	v_lshlrev_b32_e32 v178, 16, v208
	v_and_b32_e32 v208, 0xffff0000, v208
	v_lshlrev_b32_e32 v179, 16, v228
	v_and_b32_e32 v228, 0xffff0000, v228
	v_lshlrev_b32_e32 v180, 16, v209
	v_and_b32_e32 v209, 0xffff0000, v209
	v_lshlrev_b32_e32 v181, 16, v229
	v_and_b32_e32 v229, 0xffff0000, v229
	v_fmac_f32_e32 v151, v110, v150
	v_fmac_f32_e32 v226, v111, v206
	v_fmac_f32_e32 v153, v112, v152
	v_fmac_f32_e32 v227, v113, v207
	v_fmac_f32_e32 v179, v106, v178
	v_fmac_f32_e32 v228, v107, v208
	v_fmac_f32_e32 v181, v108, v180
	v_fmac_f32_e32 v229, v109, v209
	v_cvt_pk_bf16_f32 v226, v151, v226
	v_cvt_pk_bf16_f32 v227, v153, v227
	v_cvt_pk_bf16_f32 v228, v179, v228
	v_cvt_pk_bf16_f32 v229, v181, v229
	v_add_u32_e32 v146, 0x48000, v248
	global_store_dwordx4 v146, v[226:229], s[90:91]
	global_load_dwordx4 v[110:113], v249, s[90:91] offset:256
	global_load_dwordx4 v[106:109], v248, s[90:91] offset:256
	s_waitcnt vmcnt(12)
; __device__ __forceinline__ unsigned cvt_pk_bf16(float lo, float hi) { unsigned r; asm volatile("v_cvt_pk_bf16_f32 %0, %1, %2" : "=v"(r) : "v"(lo), "v"(hi)); return r; }
; __device__ __forceinline__ float fsigmoid(float x) { return __builtin_amdgcn_rcpf(1.f + __expf(-x)); }
;     __device__ __forceinline__ void operator()(const f32x4 (&acc)[2][2][4][2], const Unit& u, int wr, int wc, int fr, int fq) const {
;         const int br = u.pn >> 2, row0 = u.pm * BM + wr * 64 + fr, col0 = (u.pn & 3) * BM + wc * 32 + 8 * fq;
; #pragma unroll
;         for (int bj = 0; bj < 2; ++bj) { const f32x4 b0 = *(const f32x4*)(bg + br * 1024 + col0 + bj * HALF), b1 = *(const f32x4*)(bg + br * 1024 + col0 + bj * HALF + 4);
; #pragma unroll
;             for (int ai = 0; ai < 2; ++ai)
; #pragma unroll
;                 for (int m = 0; m < 4; ++m) { bf16_t* pm_ = G + (size_t)(row0 + ai * HALF + m * 16) * 3072 + col0 + bj * HALF;
;                     const u32x4 pv = *(const u32x4*)(pm_ + br * 1024); u32x4 mv = (u32x4){0u, 0u, 0u, 0u}; if (br) mv = *(const u32x4*)pm_;
;                     const f32x4 v0 = acc[ai][bj][m][0] + b0, v1 = acc[ai][bj][m][1] + b1;
;                     u32x4 w;
;                     w.x = cvt_pk_bf16(bf_lo(mv.x) + fsigmoid(v0[0]) * bf_lo(pv.x), bf_hi(mv.x) + fsigmoid(v0[1]) * bf_hi(pv.x));
;                     w.y = cvt_pk_bf16(bf_lo(mv.y) + fsigmoid(v0[2]) * bf_lo(pv.y), bf_hi(mv.y) + fsigmoid(v0[3]) * bf_hi(pv.y));
;                     w.z = cvt_pk_bf16(bf_lo(mv.z) + fsigmoid(v1[0]) * bf_lo(pv.z), bf_hi(mv.z) + fsigmoid(v1[1]) * bf_hi(pv.z));
;                     w.w = cvt_pk_bf16(bf_lo(mv.w) + fsigmoid(v1[2]) * bf_lo(pv.w), bf_hi(mv.w) + fsigmoid(v1[3]) * bf_hi(pv.w));
;                     *(u32x4*)pm_ = w; } }
	v_pk_add_f32 v[102:103], v[102:103], v[90:91]
	v_pk_add_f32 v[104:105], v[104:105], v[92:93]
	v_pk_add_f32 v[98:99], v[98:99], v[94:95]
	v_pk_add_f32 v[100:101], v[100:101], v[96:97]
	v_mul_f32_e32 v102, 0xbfb8aa3b, v102
	v_mul_f32_e32 v103, 0xbfb8aa3b, v103
	v_mul_f32_e32 v104, 0xbfb8aa3b, v104
	v_mul_f32_e32 v105, 0xbfb8aa3b, v105
	v_mul_f32_e32 v98, 0xbfb8aa3b, v98
	v_mul_f32_e32 v99, 0xbfb8aa3b, v99
	v_mul_f32_e32 v100, 0xbfb8aa3b, v100
	v_mul_f32_e32 v101, 0xbfb8aa3b, v101
	v_exp_f32_e32 v102, v102
	v_exp_f32_e32 v103, v103
	v_exp_f32_e32 v104, v104
	v_exp_f32_e32 v105, v105
	v_exp_f32_e32 v98, v98
	v_exp_f32_e32 v99, v99
	v_exp_f32_e32 v100, v100
	v_exp_f32_e32 v101, v101
	v_add_f32_e32 v102, 1.0, v102
	v_add_f32_e32 v103, 1.0, v103
	v_add_f32_e32 v104, 1.0, v104
	v_add_f32_e32 v105, 1.0, v105
	v_add_f32_e32 v98, 1.0, v98
	v_add_f32_e32 v99, 1.0, v99
	v_add_f32_e32 v100, 1.0, v100
	v_add_f32_e32 v101, 1.0, v101
	v_rcp_f32_e32 v102, v102
	v_rcp_f32_e32 v103, v103
	v_rcp_f32_e32 v104, v104
	v_rcp_f32_e32 v105, v105
	v_rcp_f32_e32 v98, v98
	v_rcp_f32_e32 v99, v99
	v_rcp_f32_e32 v100, v100
	v_rcp_f32_e32 v101, v101
	v_and_b32_e32 v236, s50, v236
	v_and_b32_e32 v237, s50, v237
	v_and_b32_e32 v238, s50, v238
	v_and_b32_e32 v239, s50, v239
	v_lshlrev_b32_e32 v150, 16, v210
	v_and_b32_e32 v210, 0xffff0000, v210
	v_lshlrev_b32_e32 v151, 16, v236
	v_and_b32_e32 v236, 0xffff0000, v236
	v_lshlrev_b32_e32 v152, 16, v211
	v_and_b32_e32 v211, 0xffff0000, v211
	v_lshlrev_b32_e32 v153, 16, v237
	v_and_b32_e32 v237, 0xffff0000, v237
	v_lshlrev_b32_e32 v178, 16, v212
	v_and_b32_e32 v212, 0xffff0000, v212
	v_lshlrev_b32_e32 v179, 16, v238
	v_and_b32_e32 v238, 0xffff0000, v238
	v_lshlrev_b32_e32 v180, 16, v213
	v_and_b32_e32 v213, 0xffff0000, v213
	v_lshlrev_b32_e32 v181, 16, v239
	v_and_b32_e32 v239, 0xffff0000, v239
	v_fmac_f32_e32 v151, v102, v150
	v_fmac_f32_e32 v236, v103, v210
	v_fmac_f32_e32 v153, v104, v152
	v_fmac_f32_e32 v237, v105, v211
	v_fmac_f32_e32 v179, v98, v178
	v_fmac_f32_e32 v238, v99, v212
	v_fmac_f32_e32 v181, v100, v180
	v_fmac_f32_e32 v239, v101, v213
	v_cvt_pk_bf16_f32 v236, v151, v236
	v_cvt_pk_bf16_f32 v237, v153, v237
	v_cvt_pk_bf16_f32 v238, v179, v238
	v_cvt_pk_bf16_f32 v239, v181, v239
	v_add_u32_e32 v146, 0xc0000, v248
	global_store_dwordx4 v146, v[236:239], s[90:91]
	v_add_u32_e32 v147, 0x18000, v249
	global_load_dwordx4 v[102:105], v147, s[90:91] offset:256
	v_add_u32_e32 v147, 0x18000, v248
	global_load_dwordx4 v[98:101], v147, s[90:91] offset:256
	s_waitcnt vmcnt(12)
	v_pk_add_f32 v[86:87], v[86:87], v[90:91]
	v_pk_add_f32 v[88:89], v[88:89], v[92:93]
	v_pk_add_f32 v[82:83], v[82:83], v[94:95]
	v_pk_add_f32 v[84:85], v[84:85], v[96:97]
	v_mul_f32_e32 v86, 0xbfb8aa3b, v86
	v_mul_f32_e32 v87, 0xbfb8aa3b, v87
	v_mul_f32_e32 v88, 0xbfb8aa3b, v88
	v_mul_f32_e32 v89, 0xbfb8aa3b, v89
	v_mul_f32_e32 v82, 0xbfb8aa3b, v82
	v_mul_f32_e32 v83, 0xbfb8aa3b, v83
	v_mul_f32_e32 v84, 0xbfb8aa3b, v84
	v_mul_f32_e32 v85, 0xbfb8aa3b, v85
	v_exp_f32_e32 v86, v86
	v_exp_f32_e32 v87, v87
	v_exp_f32_e32 v88, v88
	v_exp_f32_e32 v89, v89
	v_exp_f32_e32 v82, v82
	v_exp_f32_e32 v83, v83
	v_exp_f32_e32 v84, v84
	v_exp_f32_e32 v85, v85
	v_add_f32_e32 v86, 1.0, v86
	v_add_f32_e32 v87, 1.0, v87
	v_add_f32_e32 v88, 1.0, v88
	v_add_f32_e32 v89, 1.0, v89
	v_add_f32_e32 v82, 1.0, v82
	v_add_f32_e32 v83, 1.0, v83
	v_add_f32_e32 v84, 1.0, v84
	v_add_f32_e32 v85, 1.0, v85
	v_rcp_f32_e32 v86, v86
	v_rcp_f32_e32 v87, v87
	v_rcp_f32_e32 v88, v88
	v_rcp_f32_e32 v89, v89
	v_rcp_f32_e32 v82, v82
	v_rcp_f32_e32 v83, v83
	v_rcp_f32_e32 v84, v84
	v_rcp_f32_e32 v85, v85
	v_and_b32_e32 v130, s50, v130
	v_and_b32_e32 v131, s50, v131
	v_and_b32_e32 v132, s50, v132
	v_and_b32_e32 v133, s50, v133
	v_lshlrev_b32_e32 v150, 16, v134
	v_and_b32_e32 v134, 0xffff0000, v134
	v_lshlrev_b32_e32 v151, 16, v130
	v_and_b32_e32 v130, 0xffff0000, v130
	v_lshlrev_b32_e32 v152, 16, v135
	v_and_b32_e32 v135, 0xffff0000, v135
	v_lshlrev_b32_e32 v153, 16, v131
	v_and_b32_e32 v131, 0xffff0000, v131
	v_lshlrev_b32_e32 v178, 16, v136
	v_and_b32_e32 v136, 0xffff0000, v136
	v_lshlrev_b32_e32 v179, 16, v132
	v_and_b32_e32 v132, 0xffff0000, v132
	v_lshlrev_b32_e32 v180, 16, v137
	v_and_b32_e32 v137, 0xffff0000, v137
	v_lshlrev_b32_e32 v181, 16, v133
	v_and_b32_e32 v133, 0xffff0000, v133
	v_fmac_f32_e32 v151, v86, v150
	v_fmac_f32_e32 v130, v87, v134
	v_fmac_f32_e32 v153, v88, v152
	v_fmac_f32_e32 v131, v89, v135
	v_fmac_f32_e32 v179, v82, v178
	v_fmac_f32_e32 v132, v83, v136
	v_fmac_f32_e32 v181, v84, v180
	v_fmac_f32_e32 v133, v85, v137
	v_cvt_pk_bf16_f32 v130, v151, v130
	v_cvt_pk_bf16_f32 v131, v153, v131
	v_cvt_pk_bf16_f32 v132, v179, v132
	v_cvt_pk_bf16_f32 v133, v181, v133
	v_add_u32_e32 v146, 0xd8000, v248
	global_store_dwordx4 v146, v[130:133], s[90:91]
	v_add_u32_e32 v147, 0x30000, v249
	global_load_dwordx4 v[86:89], v147, s[90:91] offset:256
	v_add_u32_e32 v147, 0x30000, v248
	global_load_dwordx4 v[82:85], v147, s[90:91] offset:256
	s_waitcnt vmcnt(12)
; __device__ __forceinline__ unsigned cvt_pk_bf16(float lo, float hi) { unsigned r; asm volatile("v_cvt_pk_bf16_f32 %0, %1, %2" : "=v"(r) : "v"(lo), "v"(hi)); return r; }
; __device__ __forceinline__ float fsigmoid(float x) { return __builtin_amdgcn_rcpf(1.f + __expf(-x)); }
;     __device__ __forceinline__ void operator()(const f32x4 (&acc)[2][2][4][2], const Unit& u, int wr, int wc, int fr, int fq) const {
;         const int br = u.pn >> 2, row0 = u.pm * BM + wr * 64 + fr, col0 = (u.pn & 3) * BM + wc * 32 + 8 * fq;
; #pragma unroll
;         for (int bj = 0; bj < 2; ++bj) { const f32x4 b0 = *(const f32x4*)(bg + br * 1024 + col0 + bj * HALF), b1 = *(const f32x4*)(bg + br * 1024 + col0 + bj * HALF + 4);
; #pragma unroll
;             for (int ai = 0; ai < 2; ++ai)
; #pragma unroll
;                 for (int m = 0; m < 4; ++m) { bf16_t* pm_ = G + (size_t)(row0 + ai * HALF + m * 16) * 3072 + col0 + bj * HALF;
;                     const u32x4 pv = *(const u32x4*)(pm_ + br * 1024); u32x4 mv = (u32x4){0u, 0u, 0u, 0u}; if (br) mv = *(const u32x4*)pm_;
;                     const f32x4 v0 = acc[ai][bj][m][0] + b0, v1 = acc[ai][bj][m][1] + b1;
;                     u32x4 w;
;                     w.x = cvt_pk_bf16(bf_lo(mv.x) + fsigmoid(v0[0]) * bf_lo(pv.x), bf_hi(mv.x) + fsigmoid(v0[1]) * bf_hi(pv.x));
;                     w.y = cvt_pk_bf16(bf_lo(mv.y) + fsigmoid(v0[2]) * bf_lo(pv.y), bf_hi(mv.y) + fsigmoid(v0[3]) * bf_hi(pv.y));
;                     w.z = cvt_pk_bf16(bf_lo(mv.z) + fsigmoid(v1[0]) * bf_lo(pv.z), bf_hi(mv.z) + fsigmoid(v1[1]) * bf_hi(pv.z));
;                     w.w = cvt_pk_bf16(bf_lo(mv.w) + fsigmoid(v1[2]) * bf_lo(pv.w), bf_hi(mv.w) + fsigmoid(v1[3]) * bf_hi(pv.w));
;                     *(u32x4*)pm_ = w; } }
	v_pk_add_f32 v[78:79], v[78:79], v[90:91]
	v_pk_add_f32 v[80:81], v[80:81], v[92:93]
	v_pk_add_f32 v[74:75], v[74:75], v[94:95]
	v_pk_add_f32 v[76:77], v[76:77], v[96:97]
	v_mul_f32_e32 v78, 0xbfb8aa3b, v78
	v_mul_f32_e32 v79, 0xbfb8aa3b, v79
	v_mul_f32_e32 v80, 0xbfb8aa3b, v80
	v_mul_f32_e32 v81, 0xbfb8aa3b, v81
	v_mul_f32_e32 v74, 0xbfb8aa3b, v74
	v_mul_f32_e32 v75, 0xbfb8aa3b, v75
	v_mul_f32_e32 v76, 0xbfb8aa3b, v76
	v_mul_f32_e32 v77, 0xbfb8aa3b, v77
	v_exp_f32_e32 v78, v78
	v_exp_f32_e32 v79, v79
	v_exp_f32_e32 v80, v80
	v_exp_f32_e32 v81, v81
	v_exp_f32_e32 v74, v74
	v_exp_f32_e32 v75, v75
	v_exp_f32_e32 v76, v76
	v_exp_f32_e32 v77, v77
	v_add_f32_e32 v78, 1.0, v78
	v_add_f32_e32 v79, 1.0, v79
	v_add_f32_e32 v80, 1.0, v80
	v_add_f32_e32 v81, 1.0, v81
	v_add_f32_e32 v74, 1.0, v74
	v_add_f32_e32 v75, 1.0, v75
	v_add_f32_e32 v76, 1.0, v76
	v_add_f32_e32 v77, 1.0, v77
	v_rcp_f32_e32 v78, v78
	v_rcp_f32_e32 v79, v79
	v_rcp_f32_e32 v80, v80
	v_rcp_f32_e32 v81, v81
	v_rcp_f32_e32 v74, v74
	v_rcp_f32_e32 v75, v75
	v_rcp_f32_e32 v76, v76
	v_rcp_f32_e32 v77, v77
	v_and_b32_e32 v122, s50, v122
	v_and_b32_e32 v123, s50, v123
	v_and_b32_e32 v124, s50, v124
	v_and_b32_e32 v125, s50, v125
	v_lshlrev_b32_e32 v150, 16, v126
	v_and_b32_e32 v126, 0xffff0000, v126
	v_lshlrev_b32_e32 v151, 16, v122
	v_and_b32_e32 v122, 0xffff0000, v122
	v_lshlrev_b32_e32 v152, 16, v127
	v_and_b32_e32 v127, 0xffff0000, v127
	v_lshlrev_b32_e32 v153, 16, v123
	v_and_b32_e32 v123, 0xffff0000, v123
	v_lshlrev_b32_e32 v178, 16, v128
	v_and_b32_e32 v128, 0xffff0000, v128
	v_lshlrev_b32_e32 v179, 16, v124
	v_and_b32_e32 v124, 0xffff0000, v124
	v_lshlrev_b32_e32 v180, 16, v129
	v_and_b32_e32 v129, 0xffff0000, v129
	v_lshlrev_b32_e32 v181, 16, v125
	v_and_b32_e32 v125, 0xffff0000, v125
	v_fmac_f32_e32 v151, v78, v150
	v_fmac_f32_e32 v122, v79, v126
	v_fmac_f32_e32 v153, v80, v152
	v_fmac_f32_e32 v123, v81, v127
	v_fmac_f32_e32 v179, v74, v178
	v_fmac_f32_e32 v124, v75, v128
	v_fmac_f32_e32 v181, v76, v180
	v_fmac_f32_e32 v125, v77, v129
	v_cvt_pk_bf16_f32 v122, v151, v122
	v_cvt_pk_bf16_f32 v123, v153, v123
	v_cvt_pk_bf16_f32 v124, v179, v124
	v_cvt_pk_bf16_f32 v125, v181, v125
	v_add_u32_e32 v146, 0xf0000, v248
	global_store_dwordx4 v146, v[122:125], s[90:91]
	v_add_u32_e32 v147, 0x48000, v249
	global_load_dwordx4 v[78:81], v147, s[90:91] offset:256
	v_add_u32_e32 v147, 0x48000, v248
	global_load_dwordx4 v[74:77], v147, s[90:91] offset:256
	s_waitcnt vmcnt(12)
	v_pk_add_f32 v[70:71], v[70:71], v[90:91]
	v_pk_add_f32 v[72:73], v[72:73], v[92:93]
	v_pk_add_f32 v[66:67], v[66:67], v[94:95]
	v_pk_add_f32 v[68:69], v[68:69], v[96:97]
	v_mul_f32_e32 v70, 0xbfb8aa3b, v70
	v_mul_f32_e32 v71, 0xbfb8aa3b, v71
	v_mul_f32_e32 v72, 0xbfb8aa3b, v72
	v_mul_f32_e32 v73, 0xbfb8aa3b, v73
	v_mul_f32_e32 v66, 0xbfb8aa3b, v66
	v_mul_f32_e32 v67, 0xbfb8aa3b, v67
	v_mul_f32_e32 v68, 0xbfb8aa3b, v68
	v_mul_f32_e32 v69, 0xbfb8aa3b, v69
	v_exp_f32_e32 v70, v70
	v_exp_f32_e32 v71, v71
	v_exp_f32_e32 v72, v72
	v_exp_f32_e32 v73, v73
	v_exp_f32_e32 v66, v66
	v_exp_f32_e32 v67, v67
	v_exp_f32_e32 v68, v68
	v_exp_f32_e32 v69, v69
	v_add_f32_e32 v70, 1.0, v70
	v_add_f32_e32 v71, 1.0, v71
	v_add_f32_e32 v72, 1.0, v72
	v_add_f32_e32 v73, 1.0, v73
	v_add_f32_e32 v66, 1.0, v66
	v_add_f32_e32 v67, 1.0, v67
	v_add_f32_e32 v68, 1.0, v68
	v_add_f32_e32 v69, 1.0, v69
	v_rcp_f32_e32 v70, v70
	v_rcp_f32_e32 v71, v71
	v_rcp_f32_e32 v72, v72
	v_rcp_f32_e32 v73, v73
	v_rcp_f32_e32 v66, v66
	v_rcp_f32_e32 v67, v67
	v_rcp_f32_e32 v68, v68
	v_rcp_f32_e32 v69, v69
	v_and_b32_e32 v114, s50, v114
	v_and_b32_e32 v115, s50, v115
	v_and_b32_e32 v116, s50, v116
	v_and_b32_e32 v117, s50, v117
	v_lshlrev_b32_e32 v150, 16, v118
	v_and_b32_e32 v118, 0xffff0000, v118
	v_lshlrev_b32_e32 v151, 16, v114
	v_and_b32_e32 v114, 0xffff0000, v114
	v_lshlrev_b32_e32 v152, 16, v119
	v_and_b32_e32 v119, 0xffff0000, v119
	v_lshlrev_b32_e32 v153, 16, v115
	v_and_b32_e32 v115, 0xffff0000, v115
	v_lshlrev_b32_e32 v178, 16, v120
	v_and_b32_e32 v120, 0xffff0000, v120
	v_lshlrev_b32_e32 v179, 16, v116
	v_and_b32_e32 v116, 0xffff0000, v116
	v_lshlrev_b32_e32 v180, 16, v121
	v_and_b32_e32 v121, 0xffff0000, v121
	v_lshlrev_b32_e32 v181, 16, v117
	v_and_b32_e32 v117, 0xffff0000, v117
	v_fmac_f32_e32 v151, v70, v150
	v_fmac_f32_e32 v114, v71, v118
	v_fmac_f32_e32 v153, v72, v152
	v_fmac_f32_e32 v115, v73, v119
	v_fmac_f32_e32 v179, v66, v178
	v_fmac_f32_e32 v116, v67, v120
	v_fmac_f32_e32 v181, v68, v180
	v_fmac_f32_e32 v117, v69, v121
	v_cvt_pk_bf16_f32 v114, v151, v114
	v_cvt_pk_bf16_f32 v115, v153, v115
	v_cvt_pk_bf16_f32 v116, v179, v116
	v_cvt_pk_bf16_f32 v117, v181, v117
	v_add_u32_e32 v146, 0x108000, v248
	global_store_dwordx4 v146, v[114:117], s[90:91]
	v_add_u32_e32 v147, 0xc0000, v249
	global_load_dwordx4 v[70:73], v147, s[90:91] offset:256
	v_add_u32_e32 v147, 0xc0000, v248
	global_load_dwordx4 v[66:69], v147, s[90:91] offset:256
	s_waitcnt vmcnt(12)
; __device__ __forceinline__ unsigned cvt_pk_bf16(float lo, float hi) { unsigned r; asm volatile("v_cvt_pk_bf16_f32 %0, %1, %2" : "=v"(r) : "v"(lo), "v"(hi)); return r; }
; __device__ __forceinline__ float fsigmoid(float x) { return __builtin_amdgcn_rcpf(1.f + __expf(-x)); }
;     __device__ __forceinline__ void operator()(const f32x4 (&acc)[2][2][4][2], const Unit& u, int wr, int wc, int fr, int fq) const {
;         const int br = u.pn >> 2, row0 = u.pm * BM + wr * 64 + fr, col0 = (u.pn & 3) * BM + wc * 32 + 8 * fq;
; #pragma unroll
;         for (int bj = 0; bj < 2; ++bj) { const f32x4 b0 = *(const f32x4*)(bg + br * 1024 + col0 + bj * HALF), b1 = *(const f32x4*)(bg + br * 1024 + col0 + bj * HALF + 4);
; #pragma unroll
;             for (int ai = 0; ai < 2; ++ai)
; #pragma unroll
;                 for (int m = 0; m < 4; ++m) { bf16_t* pm_ = G + (size_t)(row0 + ai * HALF + m * 16) * 3072 + col0 + bj * HALF;
;                     const u32x4 pv = *(const u32x4*)(pm_ + br * 1024); u32x4 mv = (u32x4){0u, 0u, 0u, 0u}; if (br) mv = *(const u32x4*)pm_;
;                     const f32x4 v0 = acc[ai][bj][m][0] + b0, v1 = acc[ai][bj][m][1] + b1;
;                     u32x4 w;
;                     w.x = cvt_pk_bf16(bf_lo(mv.x) + fsigmoid(v0[0]) * bf_lo(pv.x), bf_hi(mv.x) + fsigmoid(v0[1]) * bf_hi(pv.x));
;                     w.y = cvt_pk_bf16(bf_lo(mv.y) + fsigmoid(v0[2]) * bf_lo(pv.y), bf_hi(mv.y) + fsigmoid(v0[3]) * bf_hi(pv.y));
;                     w.z = cvt_pk_bf16(bf_lo(mv.z) + fsigmoid(v1[0]) * bf_lo(pv.z), bf_hi(mv.z) + fsigmoid(v1[1]) * bf_hi(pv.z));
;                     w.w = cvt_pk_bf16(bf_lo(mv.w) + fsigmoid(v1[2]) * bf_lo(pv.w), bf_hi(mv.w) + fsigmoid(v1[3]) * bf_hi(pv.w));
;                     *(u32x4*)pm_ = w; } }
	v_pk_add_f32 v[62:63], v[62:63], v[138:139]
	v_pk_add_f32 v[64:65], v[64:65], v[140:141]
	v_pk_add_f32 v[58:59], v[58:59], v[142:143]
	v_pk_add_f32 v[60:61], v[60:61], v[144:145]
	v_mul_f32_e32 v62, 0xbfb8aa3b, v62
	v_mul_f32_e32 v63, 0xbfb8aa3b, v63
	v_mul_f32_e32 v64, 0xbfb8aa3b, v64
	v_mul_f32_e32 v65, 0xbfb8aa3b, v65
	v_mul_f32_e32 v58, 0xbfb8aa3b, v58
	v_mul_f32_e32 v59, 0xbfb8aa3b, v59
	v_mul_f32_e32 v60, 0xbfb8aa3b, v60
	v_mul_f32_e32 v61, 0xbfb8aa3b, v61
	v_exp_f32_e32 v62, v62
	v_exp_f32_e32 v63, v63
	v_exp_f32_e32 v64, v64
	v_exp_f32_e32 v65, v65
	v_exp_f32_e32 v58, v58
	v_exp_f32_e32 v59, v59
	v_exp_f32_e32 v60, v60
	v_exp_f32_e32 v61, v61
	v_add_f32_e32 v62, 1.0, v62
	v_add_f32_e32 v63, 1.0, v63
	v_add_f32_e32 v64, 1.0, v64
	v_add_f32_e32 v65, 1.0, v65
	v_add_f32_e32 v58, 1.0, v58
	v_add_f32_e32 v59, 1.0, v59
	v_add_f32_e32 v60, 1.0, v60
	v_add_f32_e32 v61, 1.0, v61
	v_rcp_f32_e32 v62, v62
	v_rcp_f32_e32 v63, v63
	v_rcp_f32_e32 v64, v64
	v_rcp_f32_e32 v65, v65
	v_rcp_f32_e32 v58, v58
	v_rcp_f32_e32 v59, v59
	v_rcp_f32_e32 v60, v60
	v_rcp_f32_e32 v61, v61
	v_and_b32_e32 v106, s50, v106
	v_and_b32_e32 v107, s50, v107
	v_and_b32_e32 v108, s50, v108
	v_and_b32_e32 v109, s50, v109
	v_lshlrev_b32_e32 v150, 16, v110
	v_and_b32_e32 v110, 0xffff0000, v110
	v_lshlrev_b32_e32 v151, 16, v106
	v_and_b32_e32 v106, 0xffff0000, v106
	v_lshlrev_b32_e32 v152, 16, v111
	v_and_b32_e32 v111, 0xffff0000, v111
	v_lshlrev_b32_e32 v153, 16, v107
	v_and_b32_e32 v107, 0xffff0000, v107
	v_lshlrev_b32_e32 v178, 16, v112
	v_and_b32_e32 v112, 0xffff0000, v112
	v_lshlrev_b32_e32 v179, 16, v108
	v_and_b32_e32 v108, 0xffff0000, v108
	v_lshlrev_b32_e32 v180, 16, v113
	v_and_b32_e32 v113, 0xffff0000, v113
	v_lshlrev_b32_e32 v181, 16, v109
	v_and_b32_e32 v109, 0xffff0000, v109
	v_fmac_f32_e32 v151, v62, v150
	v_fmac_f32_e32 v106, v63, v110
	v_fmac_f32_e32 v153, v64, v152
	v_fmac_f32_e32 v107, v65, v111
	v_fmac_f32_e32 v179, v58, v178
	v_fmac_f32_e32 v108, v59, v112
	v_fmac_f32_e32 v181, v60, v180
	v_fmac_f32_e32 v109, v61, v113
	v_cvt_pk_bf16_f32 v106, v151, v106
	v_cvt_pk_bf16_f32 v107, v153, v107
	v_cvt_pk_bf16_f32 v108, v179, v108
	v_cvt_pk_bf16_f32 v109, v181, v109
	global_store_dwordx4 v248, v[106:109], s[90:91] offset:256
	v_add_u32_e32 v147, 0xd8000, v249
	global_load_dwordx4 v[62:65], v147, s[90:91] offset:256
	v_add_u32_e32 v147, 0xd8000, v248
	global_load_dwordx4 v[58:61], v147, s[90:91] offset:256
	s_waitcnt vmcnt(12)
	v_pk_add_f32 v[54:55], v[54:55], v[138:139]
	v_pk_add_f32 v[56:57], v[56:57], v[140:141]
	v_pk_add_f32 v[50:51], v[50:51], v[142:143]
	v_pk_add_f32 v[52:53], v[52:53], v[144:145]
	v_mul_f32_e32 v54, 0xbfb8aa3b, v54
	v_mul_f32_e32 v55, 0xbfb8aa3b, v55
	v_mul_f32_e32 v56, 0xbfb8aa3b, v56
	v_mul_f32_e32 v57, 0xbfb8aa3b, v57
	v_mul_f32_e32 v50, 0xbfb8aa3b, v50
	v_mul_f32_e32 v51, 0xbfb8aa3b, v51
	v_mul_f32_e32 v52, 0xbfb8aa3b, v52
	v_mul_f32_e32 v53, 0xbfb8aa3b, v53
	v_exp_f32_e32 v54, v54
	v_exp_f32_e32 v55, v55
	v_exp_f32_e32 v56, v56
	v_exp_f32_e32 v57, v57
	v_exp_f32_e32 v50, v50
	v_exp_f32_e32 v51, v51
	v_exp_f32_e32 v52, v52
	v_exp_f32_e32 v53, v53
	v_add_f32_e32 v54, 1.0, v54
	v_add_f32_e32 v55, 1.0, v55
	v_add_f32_e32 v56, 1.0, v56
	v_add_f32_e32 v57, 1.0, v57
	v_add_f32_e32 v50, 1.0, v50
	v_add_f32_e32 v51, 1.0, v51
	v_add_f32_e32 v52, 1.0, v52
	v_add_f32_e32 v53, 1.0, v53
	v_rcp_f32_e32 v54, v54
	v_rcp_f32_e32 v55, v55
	v_rcp_f32_e32 v56, v56
	v_rcp_f32_e32 v57, v57
	v_rcp_f32_e32 v50, v50
	v_rcp_f32_e32 v51, v51
	v_rcp_f32_e32 v52, v52
	v_rcp_f32_e32 v53, v53
	v_and_b32_e32 v98, s50, v98
	v_and_b32_e32 v99, s50, v99
	v_and_b32_e32 v100, s50, v100
	v_and_b32_e32 v101, s50, v101
	v_lshlrev_b32_e32 v150, 16, v102
	v_and_b32_e32 v102, 0xffff0000, v102
	v_lshlrev_b32_e32 v151, 16, v98
	v_and_b32_e32 v98, 0xffff0000, v98
	v_lshlrev_b32_e32 v152, 16, v103
	v_and_b32_e32 v103, 0xffff0000, v103
	v_lshlrev_b32_e32 v153, 16, v99
	v_and_b32_e32 v99, 0xffff0000, v99
	v_lshlrev_b32_e32 v178, 16, v104
	v_and_b32_e32 v104, 0xffff0000, v104
	v_lshlrev_b32_e32 v179, 16, v100
	v_and_b32_e32 v100, 0xffff0000, v100
	v_lshlrev_b32_e32 v180, 16, v105
	v_and_b32_e32 v105, 0xffff0000, v105
	v_lshlrev_b32_e32 v181, 16, v101
	v_and_b32_e32 v101, 0xffff0000, v101
	v_fmac_f32_e32 v151, v54, v150
	v_fmac_f32_e32 v98, v55, v102
	v_fmac_f32_e32 v153, v56, v152
	v_fmac_f32_e32 v99, v57, v103
	v_fmac_f32_e32 v179, v50, v178
	v_fmac_f32_e32 v100, v51, v104
	v_fmac_f32_e32 v181, v52, v180
	v_fmac_f32_e32 v101, v53, v105
	v_cvt_pk_bf16_f32 v98, v151, v98
	v_cvt_pk_bf16_f32 v99, v153, v99
	v_cvt_pk_bf16_f32 v100, v179, v100
	v_cvt_pk_bf16_f32 v101, v181, v101
	v_add_u32_e32 v146, 0x18000, v248
	global_store_dwordx4 v146, v[98:101], s[90:91] offset:256
	v_add_u32_e32 v147, 0xf0000, v249
	global_load_dwordx4 v[54:57], v147, s[90:91] offset:256
	v_add_u32_e32 v147, 0xf0000, v248
	global_load_dwordx4 v[50:53], v147, s[90:91] offset:256
	s_waitcnt vmcnt(12)
; __device__ __forceinline__ unsigned cvt_pk_bf16(float lo, float hi) { unsigned r; asm volatile("v_cvt_pk_bf16_f32 %0, %1, %2" : "=v"(r) : "v"(lo), "v"(hi)); return r; }
; __device__ __forceinline__ float fsigmoid(float x) { return __builtin_amdgcn_rcpf(1.f + __expf(-x)); }
;     __device__ __forceinline__ void operator()(const f32x4 (&acc)[2][2][4][2], const Unit& u, int wr, int wc, int fr, int fq) const {
;         const int br = u.pn >> 2, row0 = u.pm * BM + wr * 64 + fr, col0 = (u.pn & 3) * BM + wc * 32 + 8 * fq;
; #pragma unroll
;         for (int bj = 0; bj < 2; ++bj) { const f32x4 b0 = *(const f32x4*)(bg + br * 1024 + col0 + bj * HALF), b1 = *(const f32x4*)(bg + br * 1024 + col0 + bj * HALF + 4);
; #pragma unroll
;             for (int ai = 0; ai < 2; ++ai)
; #pragma unroll
;                 for (int m = 0; m < 4; ++m) { bf16_t* pm_ = G + (size_t)(row0 + ai * HALF + m * 16) * 3072 + col0 + bj * HALF;
;                     const u32x4 pv = *(const u32x4*)(pm_ + br * 1024); u32x4 mv = (u32x4){0u, 0u, 0u, 0u}; if (br) mv = *(const u32x4*)pm_;
;                     const f32x4 v0 = acc[ai][bj][m][0] + b0, v1 = acc[ai][bj][m][1] + b1;
;                     u32x4 w;
;                     w.x = cvt_pk_bf16(bf_lo(mv.x) + fsigmoid(v0[0]) * bf_lo(pv.x), bf_hi(mv.x) + fsigmoid(v0[1]) * bf_hi(pv.x));
;                     w.y = cvt_pk_bf16(bf_lo(mv.y) + fsigmoid(v0[2]) * bf_lo(pv.y), bf_hi(mv.y) + fsigmoid(v0[3]) * bf_hi(pv.y));
;                     w.z = cvt_pk_bf16(bf_lo(mv.z) + fsigmoid(v1[0]) * bf_lo(pv.z), bf_hi(mv.z) + fsigmoid(v1[1]) * bf_hi(pv.z));
;                     w.w = cvt_pk_bf16(bf_lo(mv.w) + fsigmoid(v1[2]) * bf_lo(pv.w), bf_hi(mv.w) + fsigmoid(v1[3]) * bf_hi(pv.w));
;                     *(u32x4*)pm_ = w; } }
	v_pk_add_f32 v[46:47], v[46:47], v[138:139]
	v_pk_add_f32 v[48:49], v[48:49], v[140:141]
	v_pk_add_f32 v[42:43], v[42:43], v[142:143]
	v_pk_add_f32 v[44:45], v[44:45], v[144:145]
	v_mul_f32_e32 v46, 0xbfb8aa3b, v46
	v_mul_f32_e32 v47, 0xbfb8aa3b, v47
	v_mul_f32_e32 v48, 0xbfb8aa3b, v48
	v_mul_f32_e32 v49, 0xbfb8aa3b, v49
	v_mul_f32_e32 v42, 0xbfb8aa3b, v42
	v_mul_f32_e32 v43, 0xbfb8aa3b, v43
	v_mul_f32_e32 v44, 0xbfb8aa3b, v44
	v_mul_f32_e32 v45, 0xbfb8aa3b, v45
	v_exp_f32_e32 v46, v46
	v_exp_f32_e32 v47, v47
	v_exp_f32_e32 v48, v48
	v_exp_f32_e32 v49, v49
	v_exp_f32_e32 v42, v42
	v_exp_f32_e32 v43, v43
	v_exp_f32_e32 v44, v44
	v_exp_f32_e32 v45, v45
	v_add_f32_e32 v46, 1.0, v46
	v_add_f32_e32 v47, 1.0, v47
	v_add_f32_e32 v48, 1.0, v48
	v_add_f32_e32 v49, 1.0, v49
	v_add_f32_e32 v42, 1.0, v42
	v_add_f32_e32 v43, 1.0, v43
	v_add_f32_e32 v44, 1.0, v44
	v_add_f32_e32 v45, 1.0, v45
	v_rcp_f32_e32 v46, v46
	v_rcp_f32_e32 v47, v47
	v_rcp_f32_e32 v48, v48
	v_rcp_f32_e32 v49, v49
	v_rcp_f32_e32 v42, v42
	v_rcp_f32_e32 v43, v43
	v_rcp_f32_e32 v44, v44
	v_rcp_f32_e32 v45, v45
	v_and_b32_e32 v82, s50, v82
	v_and_b32_e32 v83, s50, v83
	v_and_b32_e32 v84, s50, v84
	v_and_b32_e32 v85, s50, v85
	v_lshlrev_b32_e32 v150, 16, v86
	v_and_b32_e32 v86, 0xffff0000, v86
	v_lshlrev_b32_e32 v151, 16, v82
	v_and_b32_e32 v82, 0xffff0000, v82
	v_lshlrev_b32_e32 v152, 16, v87
	v_and_b32_e32 v87, 0xffff0000, v87
	v_lshlrev_b32_e32 v153, 16, v83
	v_and_b32_e32 v83, 0xffff0000, v83
	v_lshlrev_b32_e32 v178, 16, v88
	v_and_b32_e32 v88, 0xffff0000, v88
	v_lshlrev_b32_e32 v179, 16, v84
	v_and_b32_e32 v84, 0xffff0000, v84
	v_lshlrev_b32_e32 v180, 16, v89
	v_and_b32_e32 v89, 0xffff0000, v89
	v_lshlrev_b32_e32 v181, 16, v85
	v_and_b32_e32 v85, 0xffff0000, v85
	v_fmac_f32_e32 v151, v46, v150
	v_fmac_f32_e32 v82, v47, v86
	v_fmac_f32_e32 v153, v48, v152
	v_fmac_f32_e32 v83, v49, v87
	v_fmac_f32_e32 v179, v42, v178
	v_fmac_f32_e32 v84, v43, v88
	v_fmac_f32_e32 v181, v44, v180
	v_fmac_f32_e32 v85, v45, v89
	v_cvt_pk_bf16_f32 v82, v151, v82
	v_cvt_pk_bf16_f32 v83, v153, v83
	v_cvt_pk_bf16_f32 v84, v179, v84
	v_cvt_pk_bf16_f32 v85, v181, v85
	v_add_u32_e32 v146, 0x30000, v248
	global_store_dwordx4 v146, v[82:85], s[90:91] offset:256
	v_add_u32_e32 v147, 0x108000, v249
	global_load_dwordx4 v[46:49], v147, s[90:91] offset:256
	v_add_u32_e32 v147, 0x108000, v248
	global_load_dwordx4 v[42:45], v147, s[90:91] offset:256
	s_waitcnt vmcnt(12)
	v_pk_add_f32 v[38:39], v[38:39], v[138:139]
	v_pk_add_f32 v[40:41], v[40:41], v[140:141]
	v_pk_add_f32 v[34:35], v[34:35], v[142:143]
	v_pk_add_f32 v[36:37], v[36:37], v[144:145]
	v_mul_f32_e32 v38, 0xbfb8aa3b, v38
	v_mul_f32_e32 v39, 0xbfb8aa3b, v39
	v_mul_f32_e32 v40, 0xbfb8aa3b, v40
	v_mul_f32_e32 v41, 0xbfb8aa3b, v41
	v_mul_f32_e32 v34, 0xbfb8aa3b, v34
	v_mul_f32_e32 v35, 0xbfb8aa3b, v35
	v_mul_f32_e32 v36, 0xbfb8aa3b, v36
	v_mul_f32_e32 v37, 0xbfb8aa3b, v37
	v_exp_f32_e32 v38, v38
	v_exp_f32_e32 v39, v39
	v_exp_f32_e32 v40, v40
	v_exp_f32_e32 v41, v41
	v_exp_f32_e32 v34, v34
	v_exp_f32_e32 v35, v35
	v_exp_f32_e32 v36, v36
	v_exp_f32_e32 v37, v37
	v_add_f32_e32 v38, 1.0, v38
	v_add_f32_e32 v39, 1.0, v39
	v_add_f32_e32 v40, 1.0, v40
	v_add_f32_e32 v41, 1.0, v41
	v_add_f32_e32 v34, 1.0, v34
	v_add_f32_e32 v35, 1.0, v35
	v_add_f32_e32 v36, 1.0, v36
	v_add_f32_e32 v37, 1.0, v37
	v_rcp_f32_e32 v38, v38
	v_rcp_f32_e32 v39, v39
	v_rcp_f32_e32 v40, v40
	v_rcp_f32_e32 v41, v41
	v_rcp_f32_e32 v34, v34
	v_rcp_f32_e32 v35, v35
	v_rcp_f32_e32 v36, v36
	v_rcp_f32_e32 v37, v37
	v_and_b32_e32 v74, s50, v74
	v_and_b32_e32 v75, s50, v75
	v_and_b32_e32 v76, s50, v76
	v_and_b32_e32 v77, s50, v77
	v_lshlrev_b32_e32 v150, 16, v78
	v_and_b32_e32 v78, 0xffff0000, v78
	v_lshlrev_b32_e32 v151, 16, v74
	v_and_b32_e32 v74, 0xffff0000, v74
	v_lshlrev_b32_e32 v152, 16, v79
	v_and_b32_e32 v79, 0xffff0000, v79
	v_lshlrev_b32_e32 v153, 16, v75
	v_and_b32_e32 v75, 0xffff0000, v75
	v_lshlrev_b32_e32 v178, 16, v80
	v_and_b32_e32 v80, 0xffff0000, v80
	v_lshlrev_b32_e32 v179, 16, v76
	v_and_b32_e32 v76, 0xffff0000, v76
	v_lshlrev_b32_e32 v180, 16, v81
	v_and_b32_e32 v81, 0xffff0000, v81
	v_lshlrev_b32_e32 v181, 16, v77
	v_and_b32_e32 v77, 0xffff0000, v77
	v_fmac_f32_e32 v151, v38, v150
	v_fmac_f32_e32 v74, v39, v78
	v_fmac_f32_e32 v153, v40, v152
	v_fmac_f32_e32 v75, v41, v79
	v_fmac_f32_e32 v179, v34, v178
	v_fmac_f32_e32 v76, v35, v80
	v_fmac_f32_e32 v181, v36, v180
	v_fmac_f32_e32 v77, v37, v81
	v_cvt_pk_bf16_f32 v74, v151, v74
	v_cvt_pk_bf16_f32 v75, v153, v75
	v_cvt_pk_bf16_f32 v76, v179, v76
	v_cvt_pk_bf16_f32 v77, v181, v77
	v_add_u32_e32 v146, 0x48000, v248
	global_store_dwordx4 v146, v[74:77], s[90:91] offset:256
	s_waitcnt vmcnt(10)
; __device__ __forceinline__ unsigned cvt_pk_bf16(float lo, float hi) { unsigned r; asm volatile("v_cvt_pk_bf16_f32 %0, %1, %2" : "=v"(r) : "v"(lo), "v"(hi)); return r; }
; __device__ __forceinline__ float fsigmoid(float x) { return __builtin_amdgcn_rcpf(1.f + __expf(-x)); }
;     __device__ __forceinline__ void operator()(const f32x4 (&acc)[2][2][4][2], const Unit& u, int wr, int wc, int fr, int fq) const {
;         const int br = u.pn >> 2, row0 = u.pm * BM + wr * 64 + fr, col0 = (u.pn & 3) * BM + wc * 32 + 8 * fq;
; #pragma unroll
;         for (int bj = 0; bj < 2; ++bj) { const f32x4 b0 = *(const f32x4*)(bg + br * 1024 + col0 + bj * HALF), b1 = *(const f32x4*)(bg + br * 1024 + col0 + bj * HALF + 4);
; #pragma unroll
;             for (int ai = 0; ai < 2; ++ai)
; #pragma unroll
;                 for (int m = 0; m < 4; ++m) { bf16_t* pm_ = G + (size_t)(row0 + ai * HALF + m * 16) * 3072 + col0 + bj * HALF;
;                     const u32x4 pv = *(const u32x4*)(pm_ + br * 1024); u32x4 mv = (u32x4){0u, 0u, 0u, 0u}; if (br) mv = *(const u32x4*)pm_;
;                     const f32x4 v0 = acc[ai][bj][m][0] + b0, v1 = acc[ai][bj][m][1] + b1;
;                     u32x4 w;
;                     w.x = cvt_pk_bf16(bf_lo(mv.x) + fsigmoid(v0[0]) * bf_lo(pv.x), bf_hi(mv.x) + fsigmoid(v0[1]) * bf_hi(pv.x));
;                     w.y = cvt_pk_bf16(bf_lo(mv.y) + fsigmoid(v0[2]) * bf_lo(pv.y), bf_hi(mv.y) + fsigmoid(v0[3]) * bf_hi(pv.y));
;                     w.z = cvt_pk_bf16(bf_lo(mv.z) + fsigmoid(v1[0]) * bf_lo(pv.z), bf_hi(mv.z) + fsigmoid(v1[1]) * bf_hi(pv.z));
;                     w.w = cvt_pk_bf16(bf_lo(mv.w) + fsigmoid(v1[2]) * bf_lo(pv.w), bf_hi(mv.w) + fsigmoid(v1[3]) * bf_hi(pv.w));
;                     *(u32x4*)pm_ = w; } }
	v_pk_add_f32 v[30:31], v[30:31], v[138:139]
	v_pk_add_f32 v[32:33], v[32:33], v[140:141]
	v_pk_add_f32 v[26:27], v[26:27], v[142:143]
	v_pk_add_f32 v[28:29], v[28:29], v[144:145]
	v_mul_f32_e32 v30, 0xbfb8aa3b, v30
	v_mul_f32_e32 v31, 0xbfb8aa3b, v31
	v_mul_f32_e32 v32, 0xbfb8aa3b, v32
	v_mul_f32_e32 v33, 0xbfb8aa3b, v33
	v_mul_f32_e32 v26, 0xbfb8aa3b, v26
	v_mul_f32_e32 v27, 0xbfb8aa3b, v27
	v_mul_f32_e32 v28, 0xbfb8aa3b, v28
	v_mul_f32_e32 v29, 0xbfb8aa3b, v29
	v_exp_f32_e32 v30, v30
	v_exp_f32_e32 v31, v31
	v_exp_f32_e32 v32, v32
	v_exp_f32_e32 v33, v33
	v_exp_f32_e32 v26, v26
	v_exp_f32_e32 v27, v27
	v_exp_f32_e32 v28, v28
	v_exp_f32_e32 v29, v29
	v_add_f32_e32 v30, 1.0, v30
	v_add_f32_e32 v31, 1.0, v31
	v_add_f32_e32 v32, 1.0, v32
	v_add_f32_e32 v33, 1.0, v33
	v_add_f32_e32 v26, 1.0, v26
	v_add_f32_e32 v27, 1.0, v27
	v_add_f32_e32 v28, 1.0, v28
	v_add_f32_e32 v29, 1.0, v29
	v_rcp_f32_e32 v30, v30
	v_rcp_f32_e32 v31, v31
	v_rcp_f32_e32 v32, v32
	v_rcp_f32_e32 v33, v33
	v_rcp_f32_e32 v26, v26
	v_rcp_f32_e32 v27, v27
	v_rcp_f32_e32 v28, v28
	v_rcp_f32_e32 v29, v29
	v_and_b32_e32 v66, s50, v66
	v_and_b32_e32 v67, s50, v67
	v_and_b32_e32 v68, s50, v68
	v_and_b32_e32 v69, s50, v69
	v_lshlrev_b32_e32 v150, 16, v70
	v_and_b32_e32 v70, 0xffff0000, v70
	v_lshlrev_b32_e32 v151, 16, v66
	v_and_b32_e32 v66, 0xffff0000, v66
	v_lshlrev_b32_e32 v152, 16, v71
	v_and_b32_e32 v71, 0xffff0000, v71
	v_lshlrev_b32_e32 v153, 16, v67
	v_and_b32_e32 v67, 0xffff0000, v67
	v_lshlrev_b32_e32 v178, 16, v72
	v_and_b32_e32 v72, 0xffff0000, v72
	v_lshlrev_b32_e32 v179, 16, v68
	v_and_b32_e32 v68, 0xffff0000, v68
	v_lshlrev_b32_e32 v180, 16, v73
	v_and_b32_e32 v73, 0xffff0000, v73
	v_lshlrev_b32_e32 v181, 16, v69
	v_and_b32_e32 v69, 0xffff0000, v69
	v_fmac_f32_e32 v151, v30, v150
	v_fmac_f32_e32 v66, v31, v70
	v_fmac_f32_e32 v153, v32, v152
	v_fmac_f32_e32 v67, v33, v71
	v_fmac_f32_e32 v179, v26, v178
	v_fmac_f32_e32 v68, v27, v72
	v_fmac_f32_e32 v181, v28, v180
	v_fmac_f32_e32 v69, v29, v73
	v_cvt_pk_bf16_f32 v66, v151, v66
	v_cvt_pk_bf16_f32 v67, v153, v67
	v_cvt_pk_bf16_f32 v68, v179, v68
	v_cvt_pk_bf16_f32 v69, v181, v69
	v_add_u32_e32 v146, 0xc0000, v248
	global_store_dwordx4 v146, v[66:69], s[90:91] offset:256
	s_waitcnt vmcnt(8)
	v_pk_add_f32 v[22:23], v[22:23], v[138:139]
	v_pk_add_f32 v[24:25], v[24:25], v[140:141]
	v_pk_add_f32 v[18:19], v[18:19], v[142:143]
	v_pk_add_f32 v[20:21], v[20:21], v[144:145]
	v_mul_f32_e32 v22, 0xbfb8aa3b, v22
	v_mul_f32_e32 v23, 0xbfb8aa3b, v23
	v_mul_f32_e32 v24, 0xbfb8aa3b, v24
	v_mul_f32_e32 v25, 0xbfb8aa3b, v25
	v_mul_f32_e32 v18, 0xbfb8aa3b, v18
	v_mul_f32_e32 v19, 0xbfb8aa3b, v19
	v_mul_f32_e32 v20, 0xbfb8aa3b, v20
	v_mul_f32_e32 v21, 0xbfb8aa3b, v21
	v_exp_f32_e32 v22, v22
	v_exp_f32_e32 v23, v23
	v_exp_f32_e32 v24, v24
	v_exp_f32_e32 v25, v25
	v_exp_f32_e32 v18, v18
	v_exp_f32_e32 v19, v19
	v_exp_f32_e32 v20, v20
	v_exp_f32_e32 v21, v21
	v_add_f32_e32 v22, 1.0, v22
	v_add_f32_e32 v23, 1.0, v23
	v_add_f32_e32 v24, 1.0, v24
	v_add_f32_e32 v25, 1.0, v25
	v_add_f32_e32 v18, 1.0, v18
	v_add_f32_e32 v19, 1.0, v19
	v_add_f32_e32 v20, 1.0, v20
	v_add_f32_e32 v21, 1.0, v21
	v_rcp_f32_e32 v22, v22
	v_rcp_f32_e32 v23, v23
	v_rcp_f32_e32 v24, v24
	v_rcp_f32_e32 v25, v25
	v_rcp_f32_e32 v18, v18
	v_rcp_f32_e32 v19, v19
	v_rcp_f32_e32 v20, v20
	v_rcp_f32_e32 v21, v21
	v_and_b32_e32 v58, s50, v58
	v_and_b32_e32 v59, s50, v59
	v_and_b32_e32 v60, s50, v60
	v_and_b32_e32 v61, s50, v61
	v_lshlrev_b32_e32 v150, 16, v62
	v_and_b32_e32 v62, 0xffff0000, v62
	v_lshlrev_b32_e32 v151, 16, v58
	v_and_b32_e32 v58, 0xffff0000, v58
	v_lshlrev_b32_e32 v152, 16, v63
	v_and_b32_e32 v63, 0xffff0000, v63
	v_lshlrev_b32_e32 v153, 16, v59
	v_and_b32_e32 v59, 0xffff0000, v59
	v_lshlrev_b32_e32 v178, 16, v64
	v_and_b32_e32 v64, 0xffff0000, v64
	v_lshlrev_b32_e32 v179, 16, v60
	v_and_b32_e32 v60, 0xffff0000, v60
	v_lshlrev_b32_e32 v180, 16, v65
	v_and_b32_e32 v65, 0xffff0000, v65
	v_lshlrev_b32_e32 v181, 16, v61
	v_and_b32_e32 v61, 0xffff0000, v61
	v_fmac_f32_e32 v151, v22, v150
	v_fmac_f32_e32 v58, v23, v62
	v_fmac_f32_e32 v153, v24, v152
	v_fmac_f32_e32 v59, v25, v63
	v_fmac_f32_e32 v179, v18, v178
	v_fmac_f32_e32 v60, v19, v64
	v_fmac_f32_e32 v181, v20, v180
	v_fmac_f32_e32 v61, v21, v65
	v_cvt_pk_bf16_f32 v58, v151, v58
	v_cvt_pk_bf16_f32 v59, v153, v59
	v_cvt_pk_bf16_f32 v60, v179, v60
	v_cvt_pk_bf16_f32 v61, v181, v61
	v_add_u32_e32 v146, 0xd8000, v248
	global_store_dwordx4 v146, v[58:61], s[90:91] offset:256
	s_waitcnt vmcnt(6)
; __device__ __forceinline__ unsigned cvt_pk_bf16(float lo, float hi) { unsigned r; asm volatile("v_cvt_pk_bf16_f32 %0, %1, %2" : "=v"(r) : "v"(lo), "v"(hi)); return r; }
; __device__ __forceinline__ float fsigmoid(float x) { return __builtin_amdgcn_rcpf(1.f + __expf(-x)); }
;     __device__ __forceinline__ void operator()(const f32x4 (&acc)[2][2][4][2], const Unit& u, int wr, int wc, int fr, int fq) const {
;         const int br = u.pn >> 2, row0 = u.pm * BM + wr * 64 + fr, col0 = (u.pn & 3) * BM + wc * 32 + 8 * fq;
; #pragma unroll
;         for (int bj = 0; bj < 2; ++bj) { const f32x4 b0 = *(const f32x4*)(bg + br * 1024 + col0 + bj * HALF), b1 = *(const f32x4*)(bg + br * 1024 + col0 + bj * HALF + 4);
; #pragma unroll
;             for (int ai = 0; ai < 2; ++ai)
; #pragma unroll
;                 for (int m = 0; m < 4; ++m) { bf16_t* pm_ = G + (size_t)(row0 + ai * HALF + m * 16) * 3072 + col0 + bj * HALF;
;                     const u32x4 pv = *(const u32x4*)(pm_ + br * 1024); u32x4 mv = (u32x4){0u, 0u, 0u, 0u}; if (br) mv = *(const u32x4*)pm_;
;                     const f32x4 v0 = acc[ai][bj][m][0] + b0, v1 = acc[ai][bj][m][1] + b1;
;                     u32x4 w;
;                     w.x = cvt_pk_bf16(bf_lo(mv.x) + fsigmoid(v0[0]) * bf_lo(pv.x), bf_hi(mv.x) + fsigmoid(v0[1]) * bf_hi(pv.x));
;                     w.y = cvt_pk_bf16(bf_lo(mv.y) + fsigmoid(v0[2]) * bf_lo(pv.y), bf_hi(mv.y) + fsigmoid(v0[3]) * bf_hi(pv.y));
;                     w.z = cvt_pk_bf16(bf_lo(mv.z) + fsigmoid(v1[0]) * bf_lo(pv.z), bf_hi(mv.z) + fsigmoid(v1[1]) * bf_hi(pv.z));
;                     w.w = cvt_pk_bf16(bf_lo(mv.w) + fsigmoid(v1[2]) * bf_lo(pv.w), bf_hi(mv.w) + fsigmoid(v1[3]) * bf_hi(pv.w));
;                     *(u32x4*)pm_ = w; } }
;     }
	v_pk_add_f32 v[14:15], v[14:15], v[138:139]
	v_pk_add_f32 v[16:17], v[16:17], v[140:141]
	v_pk_add_f32 v[10:11], v[10:11], v[142:143]
	v_pk_add_f32 v[12:13], v[12:13], v[144:145]
	v_mul_f32_e32 v14, 0xbfb8aa3b, v14
	v_mul_f32_e32 v15, 0xbfb8aa3b, v15
	v_mul_f32_e32 v16, 0xbfb8aa3b, v16
	v_mul_f32_e32 v17, 0xbfb8aa3b, v17
	v_mul_f32_e32 v10, 0xbfb8aa3b, v10
	v_mul_f32_e32 v11, 0xbfb8aa3b, v11
	v_mul_f32_e32 v12, 0xbfb8aa3b, v12
	v_mul_f32_e32 v13, 0xbfb8aa3b, v13
	v_exp_f32_e32 v14, v14
	v_exp_f32_e32 v15, v15
	v_exp_f32_e32 v16, v16
	v_exp_f32_e32 v17, v17
	v_exp_f32_e32 v10, v10
	v_exp_f32_e32 v11, v11
	v_exp_f32_e32 v12, v12
	v_exp_f32_e32 v13, v13
	v_add_f32_e32 v14, 1.0, v14
	v_add_f32_e32 v15, 1.0, v15
	v_add_f32_e32 v16, 1.0, v16
	v_add_f32_e32 v17, 1.0, v17
	v_add_f32_e32 v10, 1.0, v10
	v_add_f32_e32 v11, 1.0, v11
	v_add_f32_e32 v12, 1.0, v12
	v_add_f32_e32 v13, 1.0, v13
	v_rcp_f32_e32 v14, v14
	v_rcp_f32_e32 v15, v15
	v_rcp_f32_e32 v16, v16
	v_rcp_f32_e32 v17, v17
	v_rcp_f32_e32 v10, v10
	v_rcp_f32_e32 v11, v11
	v_rcp_f32_e32 v12, v12
	v_rcp_f32_e32 v13, v13
	v_and_b32_e32 v50, s50, v50
	v_and_b32_e32 v51, s50, v51
	v_and_b32_e32 v52, s50, v52
	v_and_b32_e32 v53, s50, v53
	v_lshlrev_b32_e32 v150, 16, v54
	v_and_b32_e32 v54, 0xffff0000, v54
	v_lshlrev_b32_e32 v151, 16, v50
	v_and_b32_e32 v50, 0xffff0000, v50
	v_lshlrev_b32_e32 v152, 16, v55
	v_and_b32_e32 v55, 0xffff0000, v55
	v_lshlrev_b32_e32 v153, 16, v51
	v_and_b32_e32 v51, 0xffff0000, v51
	v_lshlrev_b32_e32 v178, 16, v56
	v_and_b32_e32 v56, 0xffff0000, v56
	v_lshlrev_b32_e32 v179, 16, v52
	v_and_b32_e32 v52, 0xffff0000, v52
	v_lshlrev_b32_e32 v180, 16, v57
	v_and_b32_e32 v57, 0xffff0000, v57
	v_lshlrev_b32_e32 v181, 16, v53
	v_and_b32_e32 v53, 0xffff0000, v53
	v_fmac_f32_e32 v151, v14, v150
	v_fmac_f32_e32 v50, v15, v54
	v_fmac_f32_e32 v153, v16, v152
	v_fmac_f32_e32 v51, v17, v55
	v_fmac_f32_e32 v179, v10, v178
	v_fmac_f32_e32 v52, v11, v56
	v_fmac_f32_e32 v181, v12, v180
	v_fmac_f32_e32 v53, v13, v57
	v_cvt_pk_bf16_f32 v50, v151, v50
	v_cvt_pk_bf16_f32 v51, v153, v51
	v_cvt_pk_bf16_f32 v52, v179, v52
	v_cvt_pk_bf16_f32 v53, v181, v53
	v_add_u32_e32 v146, 0xf0000, v248
	global_store_dwordx4 v146, v[50:53], s[90:91] offset:256
	s_waitcnt vmcnt(4)
	v_pk_add_f32 v[6:7], v[6:7], v[138:139]
	v_pk_add_f32 v[8:9], v[8:9], v[140:141]
	v_pk_add_f32 v[2:3], v[2:3], v[142:143]
	v_pk_add_f32 v[4:5], v[4:5], v[144:145]
	v_mul_f32_e32 v6, 0xbfb8aa3b, v6
	v_mul_f32_e32 v7, 0xbfb8aa3b, v7
	v_mul_f32_e32 v8, 0xbfb8aa3b, v8
	v_mul_f32_e32 v9, 0xbfb8aa3b, v9
	v_mul_f32_e32 v2, 0xbfb8aa3b, v2
	v_mul_f32_e32 v3, 0xbfb8aa3b, v3
	v_mul_f32_e32 v4, 0xbfb8aa3b, v4
	v_mul_f32_e32 v5, 0xbfb8aa3b, v5
	v_exp_f32_e32 v6, v6
	v_exp_f32_e32 v7, v7
	v_exp_f32_e32 v8, v8
	v_exp_f32_e32 v9, v9
	v_exp_f32_e32 v2, v2
	v_exp_f32_e32 v3, v3
	v_exp_f32_e32 v4, v4
	v_exp_f32_e32 v5, v5
	v_add_f32_e32 v6, 1.0, v6
	v_add_f32_e32 v7, 1.0, v7
	v_add_f32_e32 v8, 1.0, v8
	v_add_f32_e32 v9, 1.0, v9
	v_add_f32_e32 v2, 1.0, v2
	v_add_f32_e32 v3, 1.0, v3
	v_add_f32_e32 v4, 1.0, v4
	v_add_f32_e32 v5, 1.0, v5
	v_rcp_f32_e32 v6, v6
	v_rcp_f32_e32 v7, v7
	v_rcp_f32_e32 v8, v8
	v_rcp_f32_e32 v9, v9
	v_rcp_f32_e32 v2, v2
	v_rcp_f32_e32 v3, v3
	v_rcp_f32_e32 v4, v4
	v_rcp_f32_e32 v5, v5
	v_and_b32_e32 v42, s50, v42
	v_and_b32_e32 v43, s50, v43
	v_and_b32_e32 v44, s50, v44
	v_and_b32_e32 v45, s50, v45
	v_lshlrev_b32_e32 v150, 16, v46
	v_and_b32_e32 v46, 0xffff0000, v46
	v_lshlrev_b32_e32 v151, 16, v42
	v_and_b32_e32 v42, 0xffff0000, v42
	v_lshlrev_b32_e32 v152, 16, v47
	v_and_b32_e32 v47, 0xffff0000, v47
	v_lshlrev_b32_e32 v153, 16, v43
	v_and_b32_e32 v43, 0xffff0000, v43
	v_lshlrev_b32_e32 v178, 16, v48
	v_and_b32_e32 v48, 0xffff0000, v48
	v_lshlrev_b32_e32 v179, 16, v44
	v_and_b32_e32 v44, 0xffff0000, v44
	v_lshlrev_b32_e32 v180, 16, v49
	v_and_b32_e32 v49, 0xffff0000, v49
	v_lshlrev_b32_e32 v181, 16, v45
	v_and_b32_e32 v45, 0xffff0000, v45
	v_fmac_f32_e32 v151, v6, v150
	v_fmac_f32_e32 v42, v7, v46
	v_fmac_f32_e32 v153, v8, v152
	v_fmac_f32_e32 v43, v9, v47
	v_fmac_f32_e32 v179, v2, v178
	v_fmac_f32_e32 v44, v3, v48
	v_fmac_f32_e32 v181, v4, v180
	v_fmac_f32_e32 v45, v5, v49
	v_cvt_pk_bf16_f32 v42, v151, v42
	v_cvt_pk_bf16_f32 v43, v153, v43
	v_cvt_pk_bf16_f32 v44, v179, v44
	v_cvt_pk_bf16_f32 v45, v181, v45
	v_add_u32_e32 v146, 0x108000, v248
	global_store_dwordx4 v146, v[42:45], s[90:91] offset:256
	s_andn2_b64 vcc, exec, s[42:43]
	s_mov_b64 s[38:39], -1
	s_cbranch_vccnz .LBB0_265
	s_andn2_b64 vcc, exec, s[0:1]
	s_cbranch_vccnz .LBB0_264
	s_barrier
	s_branch .LBB0_264
